# LayerNorm row loop: adaLN shift/scale reload (batch change) issued at the top of the iteration instead of right before use
# speedup vs baseline: 1.0009x; 1.0009x over previous
; DI float hlo(unsigned u) { return (float)__builtin_bit_cast(f16x2_t, u).x; }
; DI float hhi(unsigned u) { return (float)__builtin_bit_cast(f16x2_t, u).y; }
; DI void lnmod_phase(const Args& A, LAS unsigned char* lds, int tid, int bid, int G, bool init, int l_norm, int i_norm, int l_mod, int i_mod, bool want_dt, int nrows, bool ctx_partial, const float* gprev, const float* bprev) {
;     ...
;         for (int j = 0; j < 4; ++j) v[j] = init ? fn[j] : (f32x4){hlo(un[j].x), hhi(un[j].x), hlo(un[j].y), hhi(un[j].y)};
;         { const int rown = row + G * 8;
;           if (rown < nrows) {
;               if (init) { const float* xin = rown < M_LAT ? A.in[I_X] + (size_t)rown * DM : A.in[I_CTX] + (size_t)(rown - M_LAT) * DM;
; #pragma unroll
;                   for (int j = 0; j < 4; ++j) fn[j] = *(const f32x4*)(xin + 256 * j + 4 * lane); }
;               else {
; #pragma unroll
;                   for (int j = 0; j < 4; ++j) un[j] = *(const u32x2*)(X16 + (size_t)rown * DM + 256 * j + 4 * lane); } } }
;         f32x2* STAT = (f32x2*)(A.ws + WS_STAT);
;         if (ctx_partial && row >= M_LAT) {
;             { const f32x2 st = STAT[row];
; #pragma unroll
;               for (int j = 0; j < 4; ++j) v[j] = (v[j] - st.x) * st.y * *(const f32x4*)(gprev + 256 * j + 4 * lane) + *(const f32x4*)(bprev + 256 * j + 4 * lane); }
;     ...
;             const int mi = row < M_LAT ? (row >> 12) : 8;
;             const float* mp = MOD + ((size_t)l_mod * 9 + mi) * 9216 + i_mod * 3072;
;             if (mi != mi_cur) { mi_cur = mi;
; #pragma unroll
;                 for (int j = 0; j < 4; ++j) { shv[j] = *(const f32x4*)(mp + 256 * j + 4 * lane); sclv[j] = *(const f32x4*)(mp + 1024 + 256 * j + 4 * lane) + 1.0f; } }
.LBB0_207:
	s_or_b64 exec, exec, s[6:7]
	s_mov_b64 s[76:77], 0
	v_min_i32_e32 v248, 0x8000, v86
	v_ashrrev_i32_e32 v248, 12, v248
	v_cmp_ne_u32_e32 vcc, v248, v117
	s_mov_b64 s[76:77], vcc
	s_and_saveexec_b64 s[78:79], vcc
	s_cbranch_execz .Llnmi_done0
	v_readlane_b32 s80, v251, 59
	v_readlane_b32 s81, v251, 60
	v_ashrrev_i32_e32 v249, 31, v248
	v_lshl_add_u64 v[32:33], s[22:23], 0, v[248:249]
	v_lshlrev_b32_e32 v246, 2, v66
	v_mov_b32_e32 v247, v147
	v_mov_b64_e32 v[34:35], s[80:81]
	v_mad_u64_u32 v[34:35], s[82:83], v32, s94, v[34:35]
	v_mad_i32_i24 v35, v33, s94, v35
	v_lshl_add_u64 v[32:33], v[34:35], 0, v[246:247]
	s_mov_b64 s[82:83], 0x1000
	v_lshl_add_u64 v[34:35], v[32:33], 0, s[82:83]
	global_load_dwordx4 v[48:51], v[34:35], off offset:1024
	global_load_dwordx4 v[52:55], v[34:35], off offset:2048
	v_mov_b32_e32 v117, v248
	global_load_dwordx4 v[56:59], v[34:35], off
	global_load_dwordx4 v[60:63], v[34:35], off offset:3072
	global_load_dwordx4 v[44:47], v[32:33], off
	global_load_dwordx4 v[40:43], v[32:33], off offset:1024
	global_load_dwordx4 v[36:39], v[32:33], off offset:2048
	global_load_dwordx4 v[32:35], v[32:33], off offset:3072
.Llnmi_done0:
	s_or_b64 exec, exec, s[78:79]
	v_cvt_f32_f16_sdwa v106, v92 dst_sel:DWORD dst_unused:UNUSED_PAD src0_sel:WORD_1
	v_cvt_f32_f16_e32 v90, v92
	v_cvt_f32_f16_sdwa v91, v93 dst_sel:DWORD dst_unused:UNUSED_PAD src0_sel:WORD_1
	v_cvt_f32_f16_e32 v107, v93
	v_cvt_f32_f16_sdwa v102, v94 dst_sel:DWORD dst_unused:UNUSED_PAD src0_sel:WORD_1
	v_cvt_f32_f16_e32 v92, v94
	v_cvt_f32_f16_sdwa v93, v95 dst_sel:DWORD dst_unused:UNUSED_PAD src0_sel:WORD_1
	v_cvt_f32_f16_e32 v103, v95
	v_cvt_f32_f16_sdwa v97, v98 dst_sel:DWORD dst_unused:UNUSED_PAD src0_sel:WORD_1
	v_cvt_f32_f16_e32 v96, v98
	v_cvt_f32_f16_sdwa v95, v99 dst_sel:DWORD dst_unused:UNUSED_PAD src0_sel:WORD_1
	v_cvt_f32_f16_e32 v94, v99
	v_cvt_f32_f16_sdwa v104, v88 dst_sel:DWORD dst_unused:UNUSED_PAD src0_sel:WORD_1
	v_cvt_f32_f16_e32 v100, v88
	v_cvt_f32_f16_sdwa v108, v89 dst_sel:DWORD dst_unused:UNUSED_PAD src0_sel:WORD_1
	v_cvt_f32_f16_e32 v98, v89
	v_readlane_b32 s36, v253, 23
	s_movk_i32 s6, 0x7fff
	v_readlane_b32 s38, v253, 25
	v_readlane_b32 s39, v253, 26
	v_cmp_lt_i32_e32 vcc, s6, v86
	v_readlane_b32 s37, v253, 24
	v_lshl_add_u64 v[88:89], s[38:39], 0, v[64:65]
	s_and_saveexec_b64 s[6:7], vcc
	s_cbranch_execz .LBB0_209
	v_readlane_b32 s38, v253, 25
	v_readlane_b32 s39, v253, 26
	v_add_u32_e32 v146, 0xffff8000, v86
	s_nop 1
	v_lshl_add_u64 v[110:111], s[38:39], 0, v[74:75]
	global_load_dwordx2 v[122:123], v[110:111], off
	v_readlane_b32 s36, v251, 61
	v_readlane_b32 s37, v251, 62
	s_mov_b32 s19, 0x800000
	global_load_dwordx4 v[172:175], v[68:69], off
	global_load_dwordx4 v[118:121], v[70:71], off
	global_load_dwordx4 v[176:179], v[68:69], off offset:1024
	global_load_dwordx4 v[180:183], v[70:71], off offset:1024
	global_load_dwordx4 v[184:187], v[68:69], off offset:2048
	global_load_dwordx4 v[188:191], v[70:71], off offset:2048
	global_load_dwordx4 v[192:195], v[68:69], off offset:3072
	global_load_dwordx4 v[196:199], v[70:71], off offset:3072
	s_waitcnt vmcnt(8)
	v_sub_f32_e32 v111, v106, v122
	v_sub_f32_e32 v110, v90, v122
	v_sub_f32_e32 v90, v107, v122
	v_pk_mul_f32 v[106:107], v[122:123], v[110:111] op_sel:[1,0]
	v_sub_f32_e32 v91, v91, v122
	v_pk_mul_f32 v[90:91], v[122:123], v[90:91] op_sel:[1,0]
	v_sub_f32_e32 v93, v93, v122
	v_sub_f32_e32 v97, v97, v122
	v_sub_f32_e32 v96, v96, v122
	v_sub_f32_e32 v95, v95, v122
	v_sub_f32_e32 v94, v94, v122
	v_sub_f32_e32 v101, v104, v122
	v_sub_f32_e32 v100, v100, v122
	v_sub_f32_e32 v99, v108, v122
	v_sub_f32_e32 v98, v98, v122
	v_pk_mul_f32 v[108:109], v[122:123], v[100:101] op_sel:[1,0]
	s_waitcnt vmcnt(6)
	v_pk_fma_f32 v[126:127], v[172:173], v[106:107], v[118:119]
	v_pk_fma_f32 v[90:91], v[174:175], v[90:91], v[120:121]
	v_sub_f32_e32 v107, v102, v122
	v_sub_f32_e32 v106, v92, v122
	v_sub_f32_e32 v92, v103, v122
	v_pk_mul_f32 v[102:103], v[122:123], v[92:93] op_sel:[1,0]
	v_pk_mul_f32 v[92:93], v[122:123], v[106:107] op_sel:[1,0]
	v_pk_mul_f32 v[106:107], v[122:123], v[96:97] op_sel:[1,0]
	s_waitcnt vmcnt(4)
	v_pk_fma_f32 v[92:93], v[92:93], v[176:177], v[180:181]
	v_pk_fma_f32 v[176:177], v[102:103], v[178:179], v[182:183]
	v_pk_mul_f32 v[102:103], v[122:123], v[94:95] op_sel:[1,0]
	s_waitcnt vmcnt(2)
	v_pk_fma_f32 v[184:185], v[106:107], v[184:185], v[188:189]
	v_pk_fma_f32 v[186:187], v[102:103], v[186:187], v[190:191]
	v_pk_mul_f32 v[106:107], v[122:123], v[98:99] op_sel:[1,0]
	s_waitcnt vmcnt(0)
; DI unsigned pkh2(float lo, float hi) { return __builtin_bit_cast(unsigned, __builtin_amdgcn_cvt_pkrtz(lo, hi)); }
; DI void lnmod_phase(const Args& A, LAS unsigned char* lds, int tid, int bid, int G, bool init, int l_norm, int i_norm, int l_mod, int i_mod, bool want_dt, int nrows, bool ctx_partial, const float* gprev, const float* bprev) {
;     ...
;             const float* t0 = (const float*)(A.ws + WS_T) + (size_t)(row - M_LAT) * DM; const float* t1 = t0 + (size_t)M_CTX * DM; const float* t2 = t1 + (size_t)M_CTX * DM; const float* t3 = t2 + (size_t)M_CTX * DM;
; #pragma unroll
;             for (int j = 0; j < 4; ++j) { v[j] = v[j] * ALPHA + (*(const f32x4*)(t0 + 256 * j + 4 * lane) + *(const f32x4*)(t1 + 256 * j + 4 * lane)) + (*(const f32x4*)(t2 + 256 * j + 4 * lane) + *(const f32x4*)(t3 + 256 * j + 4 * lane)); u32x2 w_; w_.x = pkh2(v[j].x, v[j].y); w_.y = pkh2(v[j].z, v[j].w); *(u32x2*)(xout + 256 * j + 4 * lane) = w_; }
	v_pk_fma_f32 v[192:193], v[108:109], v[192:193], v[196:197]
	v_lshlrev_b64 v[102:103], 12, v[146:147]
	v_lshl_add_u64 v[102:103], s[36:37], 0, v[102:103]
	v_lshlrev_b32_e32 v146, 2, v66
	v_lshl_add_u64 v[108:109], v[102:103], 0, v[146:147]
	v_add_co_u32_e32 v172, vcc, s19, v108
	global_load_dwordx4 v[118:121], v[108:109], off
	s_nop 1
	v_addc_co_u32_e32 v173, vcc, 0, v109, vcc
	global_load_dwordx4 v[122:125], v[172:173], off
	s_mov_b64 s[36:37], 0x800000
	v_lshl_add_u64 v[112:113], v[108:109], 0, s[36:37]
	s_mov_b64 s[36:37], 0x1000000
	v_lshl_add_u64 v[174:175], v[108:109], 0, s[36:37]
	s_mov_b64 s[36:37], 0x1800000
	v_lshl_add_u64 v[180:181], v[108:109], 0, s[36:37]
	s_mov_b32 s19, 0x1000000
	v_add_co_u32_e32 v182, vcc, s19, v108
	s_mov_b32 s19, 0x1800000
	s_nop 1
	v_addc_co_u32_e32 v183, vcc, 0, v109, vcc
	global_load_dwordx4 v[188:191], v[182:183], off
	v_add_co_u32_e32 v200, vcc, s19, v108
	s_nop 1
	v_addc_co_u32_e32 v201, vcc, 0, v109, vcc
	global_load_dwordx4 v[202:205], v[200:201], off
	global_load_dwordx4 v[218:221], v[108:109], off offset:1024
	global_load_dwordx4 v[222:225], v[112:113], off offset:1024
	global_load_dwordx4 v[226:229], v[174:175], off offset:1024
	global_load_dwordx4 v[230:233], v[180:181], off offset:1024
	s_nop 0
	v_pk_fma_f32 v[194:195], v[106:107], v[194:195], v[198:199]
	s_mov_b32 s36, 0x3fd744fd
	s_waitcnt vmcnt(6)
	v_pk_add_f32 v[172:173], v[120:121], v[124:125]
	s_nop 0
	v_pk_fma_f32 v[90:91], v[90:91], s[36:37], v[172:173] op_sel_hi:[1,0,1]
	s_nop 0
	v_pk_add_f32 v[114:115], v[118:119], v[122:123]
	v_pk_fma_f32 v[114:115], v[126:127], s[36:37], v[114:115] op_sel_hi:[1,0,1]
	s_nop 0
	s_mov_b32 s19, 0x21200000
	s_waitcnt vmcnt(4)
	v_pk_add_f32 v[200:201], v[190:191], v[204:205]
	v_pk_add_f32 v[188:189], v[188:189], v[202:203]
	v_pk_add_f32 v[200:201], v[90:91], v[200:201]
	v_pk_add_f32 v[90:91], v[114:115], v[188:189]
	v_add_co_u32_e32 v114, vcc, s19, v88
	v_cvt_pkrtz_f16_f32 v188, v90, v91
	v_cvt_pkrtz_f16_f32 v189, v200, v201
	v_addc_co_u32_e32 v115, vcc, 0, v89, vcc
	global_store_dwordx2 v[114:115], v[188:189], off
	s_nop 0
	s_waitcnt vmcnt(3)
	v_pk_add_f32 v[220:221], v[220:221], v[224:225]
	v_pk_add_f32 v[218:219], v[218:219], v[222:223]
	v_pk_fma_f32 v[176:177], v[176:177], s[36:37], v[220:221] op_sel_hi:[1,0,1]
	v_pk_fma_f32 v[92:93], v[92:93], s[36:37], v[218:219] op_sel_hi:[1,0,1]
	s_waitcnt vmcnt(1)
	v_pk_add_f32 v[228:229], v[228:229], v[232:233]
	v_pk_add_f32 v[226:227], v[226:227], v[230:231]
	v_pk_add_f32 v[126:127], v[176:177], v[228:229]
	v_pk_add_f32 v[92:93], v[92:93], v[226:227]
	v_cvt_pkrtz_f16_f32 v177, v126, v127
	v_cvt_pkrtz_f16_f32 v176, v92, v93
	global_store_dwordx2 v[114:115], v[176:177], off offset:512
	global_load_dwordx4 v[118:121], v[108:109], off offset:2048
	global_load_dwordx4 v[122:125], v[112:113], off offset:2048
	global_load_dwordx4 v[176:179], v[174:175], off offset:2048
	global_load_dwordx4 v[188:191], v[180:181], off offset:2048
	global_load_dwordx4 v[196:199], v[108:109], off offset:3072
	global_load_dwordx4 v[202:205], v[112:113], off offset:3072
	global_load_dwordx4 v[218:221], v[174:175], off offset:3072
	global_load_dwordx4 v[104:107], v[180:181], off offset:3072
	s_waitcnt vmcnt(6)
	v_pk_add_f32 v[110:111], v[120:121], v[124:125]
	v_pk_add_f32 v[118:119], v[118:119], v[122:123]
	v_pk_fma_f32 v[110:111], v[186:187], s[36:37], v[110:111] op_sel_hi:[1,0,1]
	v_pk_fma_f32 v[122:123], v[184:185], s[36:37], v[118:119] op_sel_hi:[1,0,1]
	s_waitcnt vmcnt(4)
	v_pk_add_f32 v[178:179], v[178:179], v[190:191]
	v_pk_add_f32 v[188:189], v[176:177], v[188:189]
	v_pk_add_f32 v[176:177], v[110:111], v[178:179]
	v_pk_add_f32 v[178:179], v[122:123], v[188:189]
	v_cvt_pkrtz_f16_f32 v111, v176, v177
	v_cvt_pkrtz_f16_f32 v110, v178, v179
	global_store_dwordx2 v[114:115], v[110:111], off offset:1024
	s_nop 0
	s_waitcnt vmcnt(3)
	v_pk_add_f32 v[198:199], v[198:199], v[204:205]
	v_pk_add_f32 v[196:197], v[196:197], v[202:203]
	v_pk_fma_f32 v[198:199], v[194:195], s[36:37], v[198:199] op_sel_hi:[1,0,1]
	v_pk_fma_f32 v[196:197], v[192:193], s[36:37], v[196:197] op_sel_hi:[1,0,1]
	s_nop 0
	s_waitcnt vmcnt(1)
	v_pk_add_f32 v[220:221], v[220:221], v[106:107]
	v_pk_add_f32 v[104:105], v[218:219], v[104:105]
	v_pk_add_f32 v[218:219], v[198:199], v[220:221]
	v_pk_add_f32 v[220:221], v[196:197], v[104:105]
	v_cvt_pkrtz_f16_f32 v105, v218, v219
	v_cvt_pkrtz_f16_f32 v104, v220, v221
	global_store_dwordx2 v[114:115], v[104:105], off offset:1536
	v_mov_b32_e32 v106, v91
	v_mov_b32_e32 v107, v200
	v_mov_b32_e32 v91, v201
	v_mov_b32_e32 v200, v93
	v_mov_b32_e32 v201, v126
	v_mov_b32_e32 v93, v127
	v_mov_b32_e32 v104, v221
	v_mov_b32_e32 v196, v219
	v_mov_b32_e32 v94, v176
	v_mov_b32_e32 v95, v177
	v_mov_b32_e32 v96, v178
	v_mov_b32_e32 v97, v179
	v_mov_b32_e32 v98, v218
	v_mov_b32_e32 v100, v220
	v_mov_b32_e32 v102, v200
	v_mov_b32_e32 v103, v201
	v_mov_b32_e32 v108, v196

; DI void lnmod_phase(const Args& A, LAS unsigned char* lds, int tid, int bid, int G, bool init, int l_norm, int i_norm, int l_mod, int i_mod, bool want_dt, int nrows, bool ctx_partial, const float* gprev, const float* bprev) {
;     ...
;         if (l_mod >= 0) {
;             const int mi = row < M_LAT ? (row >> 12) : 8;
;             const float* mp = MOD + ((size_t)l_mod * 9 + mi) * 9216 + i_mod * 3072;
;             if (mi != mi_cur) { mi_cur = mi;
; #pragma unroll
;                 for (int j = 0; j < 4; ++j) { shv[j] = *(const f32x4*)(mp + 256 * j + 4 * lane); sclv[j] = *(const f32x4*)(mp + 1024 + 256 * j + 4 * lane) + 1.0f; } }
.LBB0_212:
	s_or_b64 exec, exec, s[6:7]
	v_min_i32_e32 v86, 0x8000, v86
	v_ashrrev_i32_e32 v86, 12, v86
	s_mov_b64 vcc, s[76:77]
	s_and_saveexec_b64 s[6:7], vcc
	s_cbranch_execz .LBB0_214
	v_readlane_b32 s36, v251, 59
	v_readlane_b32 s37, v251, 60
	s_waitcnt vmcnt(7)
	v_pk_add_f32 v[50:51], v[50:51], 1.0 op_sel_hi:[1,0]
	v_pk_add_f32 v[48:49], v[48:49], 1.0 op_sel_hi:[1,0]
	s_waitcnt vmcnt(6)
	v_pk_add_f32 v[54:55], v[54:55], 1.0 op_sel_hi:[1,0]
	v_pk_add_f32 v[52:53], v[52:53], 1.0 op_sel_hi:[1,0]
	s_waitcnt vmcnt(5)
	v_pk_add_f32 v[58:59], v[58:59], 1.0 op_sel_hi:[1,0]
	v_pk_add_f32 v[56:57], v[56:57], 1.0 op_sel_hi:[1,0]
	s_waitcnt vmcnt(4)
	v_pk_add_f32 v[62:63], v[62:63], 1.0 op_sel_hi:[1,0]
	v_pk_add_f32 v[60:61], v[60:61], 1.0 op_sel_hi:[1,0]

; DI void lnmod_phase(const Args& A, LAS unsigned char* lds, int tid, int bid, int G, bool init, int l_norm, int i_norm, int l_mod, int i_mod, bool want_dt, int nrows, bool ctx_partial, const float* gprev, const float* bprev) {
;     ...
;         if (l_mod >= 0) {
;             const int mi = row < M_LAT ? (row >> 12) : 8;
;             const float* mp = MOD + ((size_t)l_mod * 9 + mi) * 9216 + i_mod * 3072;
;             if (mi != mi_cur) { mi_cur = mi;
; #pragma unroll
;                 for (int j = 0; j < 4; ++j) { shv[j] = *(const f32x4*)(mp + 256 * j + 4 * lane); sclv[j] = *(const f32x4*)(mp + 1024 + 256 * j + 4 * lane) + 1.0f; } }
.LBB0_231:
	s_or_b64 exec, exec, s[4:5]
	s_mov_b64 s[76:77], 0
	s_andn2_b64 vcc, exec, s[16:17]
	s_cbranch_vccnz .Llnmi_skip1
	v_min_i32_e32 v248, 0x8000, v118
	v_ashrrev_i32_e32 v248, 12, v248
	v_cmp_ne_u32_e32 vcc, v248, v117
	s_mov_b64 s[76:77], vcc
	s_and_saveexec_b64 s[78:79], vcc
	s_cbranch_execz .Llnmi_done1
	v_readlane_b32 s80, v253, 25
	v_readlane_b32 s81, v253, 26
	v_ashrrev_i32_e32 v249, 31, v248
	v_lshl_add_u64 v[32:33], s[22:23], 0, v[248:249]
	v_lshlrev_b32_e32 v246, 2, v84
	v_mov_b32_e32 v247, v147
	v_mov_b64_e32 v[34:35], s[80:81]
	v_mad_u64_u32 v[34:35], s[82:83], v32, s94, v[34:35]
	v_mad_i32_i24 v35, v33, s94, v35
	v_lshl_add_u64 v[32:33], v[34:35], 0, v[246:247]
	s_mov_b64 s[82:83], 0x1000
	v_lshl_add_u64 v[34:35], v[32:33], 0, s[82:83]
	global_load_dwordx4 v[48:51], v[34:35], off offset:1024
	global_load_dwordx4 v[52:55], v[34:35], off offset:2048
	v_mov_b32_e32 v117, v248
	global_load_dwordx4 v[56:59], v[34:35], off
	global_load_dwordx4 v[60:63], v[34:35], off offset:3072
	global_load_dwordx4 v[44:47], v[32:33], off
	global_load_dwordx4 v[40:43], v[32:33], off offset:1024
	global_load_dwordx4 v[36:39], v[32:33], off offset:2048
	global_load_dwordx4 v[32:35], v[32:33], off offset:3072

; DI float hlo(unsigned u) { return (float)__builtin_bit_cast(f16x2_t, u).x; }
; DI float hhi(unsigned u) { return (float)__builtin_bit_cast(f16x2_t, u).y; }
; DI void lnmod_phase(const Args& A, LAS unsigned char* lds, int tid, int bid, int G, bool init, int l_norm, int i_norm, int l_mod, int i_mod, bool want_dt, int nrows, bool ctx_partial, const float* gprev, const float* bprev) {
;     ...
;         for (int j = 0; j < 4; ++j) v[j] = init ? fn[j] : (f32x4){hlo(un[j].x), hhi(un[j].x), hlo(un[j].y), hhi(un[j].y)};
;         { const int rown = row + G * 8;
;           if (rown < nrows) {
;               if (init) { const float* xin = rown < M_LAT ? A.in[I_X] + (size_t)rown * DM : A.in[I_CTX] + (size_t)(rown - M_LAT) * DM;
; #pragma unroll
;                   for (int j = 0; j < 4; ++j) fn[j] = *(const f32x4*)(xin + 256 * j + 4 * lane); }
;               else {
; #pragma unroll
;                   for (int j = 0; j < 4; ++j) un[j] = *(const u32x2*)(X16 + (size_t)rown * DM + 256 * j + 4 * lane); } } }
;         f32x2* STAT = (f32x2*)(A.ws + WS_STAT);
;         if (ctx_partial && row >= M_LAT) {
;             { const f32x2 st = STAT[row];
; #pragma unroll
;               for (int j = 0; j < 4; ++j) v[j] = (v[j] - st.x) * st.y * *(const f32x4*)(gprev + 256 * j + 4 * lane) + *(const f32x4*)(bprev + 256 * j + 4 * lane); }
.Llnmi_skip1:
	v_cvt_f32_f16_sdwa v108, v66 dst_sel:DWORD dst_unused:UNUSED_PAD src0_sel:WORD_1
	v_cvt_f32_f16_e32 v64, v66
	v_cvt_f32_f16_sdwa v65, v67 dst_sel:DWORD dst_unused:UNUSED_PAD src0_sel:WORD_1
	v_cvt_f32_f16_e32 v109, v67
	v_cvt_f32_f16_sdwa v66, v72 dst_sel:DWORD dst_unused:UNUSED_PAD src0_sel:WORD_1
	v_cvt_f32_f16_e32 v68, v72
	v_cvt_f32_f16_sdwa v69, v73 dst_sel:DWORD dst_unused:UNUSED_PAD src0_sel:WORD_1
	v_cvt_f32_f16_e32 v67, v73
	v_cvt_f32_f16_sdwa v73, v70 dst_sel:DWORD dst_unused:UNUSED_PAD src0_sel:WORD_1
	v_cvt_f32_f16_e32 v72, v70
	v_cvt_f32_f16_sdwa v75, v71 dst_sel:DWORD dst_unused:UNUSED_PAD src0_sel:WORD_1
	v_cvt_f32_f16_e32 v74, v71
	v_cvt_f32_f16_sdwa v70, v76 dst_sel:DWORD dst_unused:UNUSED_PAD src0_sel:WORD_1
	v_cvt_f32_f16_e32 v76, v76
	v_cvt_f32_f16_sdwa v106, v77 dst_sel:DWORD dst_unused:UNUSED_PAD src0_sel:WORD_1
	v_cvt_f32_f16_e32 v78, v77
	s_movk_i32 s4, 0x7fff
	v_cmp_lt_i32_e32 vcc, s4, v118
	v_readlane_b32 s4, v253, 37
	v_readlane_b32 s40, v253, 23
	v_readlane_b32 s5, v253, 38
	v_readlane_b32 s42, v253, 25
	v_readlane_b32 s43, v253, 26
	s_and_b64 s[36:37], s[4:5], vcc
	v_readlane_b32 s41, v253, 24
	v_lshl_add_u64 v[104:105], s[42:43], 0, v[82:83]
	s_and_saveexec_b64 s[4:5], s[36:37]
	s_cbranch_execz .LBB0_233
	v_readlane_b32 s38, v253, 25
	v_readlane_b32 s39, v253, 26
	v_add_u32_e32 v146, 0xffff8000, v118
	s_nop 1
	v_lshl_add_u64 v[110:111], s[38:39], 0, v[92:93]
	global_load_dwordx2 v[120:121], v[110:111], off
	v_readlane_b32 s36, v251, 61
	v_readlane_b32 s37, v251, 62
	s_mov_b32 s7, 0x800000
	global_load_dwordx4 v[130:133], v[86:87], off
	global_load_dwordx4 v[112:115], v[88:89], off
	global_load_dwordx4 v[134:137], v[86:87], off offset:1024
	global_load_dwordx4 v[138:141], v[88:89], off offset:1024
	global_load_dwordx4 v[154:157], v[86:87], off offset:2048
	global_load_dwordx4 v[160:163], v[88:89], off offset:2048
	global_load_dwordx4 v[164:167], v[86:87], off offset:3072
	global_load_dwordx4 v[168:171], v[88:89], off offset:3072
	s_waitcnt vmcnt(8)
	v_sub_f32_e32 v111, v108, v120
	v_sub_f32_e32 v110, v64, v120
	v_sub_f32_e32 v64, v109, v120
	v_pk_mul_f32 v[122:123], v[120:121], v[110:111] op_sel:[1,0]
	v_sub_f32_e32 v65, v65, v120
	v_pk_mul_f32 v[64:65], v[120:121], v[64:65] op_sel:[1,0]
	v_sub_f32_e32 v69, v69, v120
	s_waitcnt vmcnt(6)
	v_pk_fma_f32 v[114:115], v[132:133], v[64:65], v[114:115]
	v_sub_f32_e32 v65, v66, v120
	v_sub_f32_e32 v64, v68, v120
	v_sub_f32_e32 v68, v67, v120
	v_pk_fma_f32 v[128:129], v[130:131], v[122:123], v[112:113]
	v_pk_mul_f32 v[112:113], v[120:121], v[68:69] op_sel:[1,0]
	v_pk_mul_f32 v[68:69], v[120:121], v[64:65] op_sel:[1,0]
	s_waitcnt vmcnt(4)
	v_pk_fma_f32 v[68:69], v[68:69], v[134:135], v[138:139]
	v_pk_fma_f32 v[138:139], v[112:113], v[136:137], v[140:141]
	v_sub_f32_e32 v135, v73, v120
	v_sub_f32_e32 v134, v72, v120
	v_sub_f32_e32 v137, v75, v120
	v_sub_f32_e32 v136, v74, v120
	v_pk_mul_f32 v[140:141], v[120:121], v[136:137] op_sel:[1,0]
	v_pk_mul_f32 v[112:113], v[120:121], v[134:135] op_sel:[1,0]
	s_waitcnt vmcnt(2)
	v_pk_fma_f32 v[160:161], v[112:113], v[154:155], v[160:161]
	v_pk_fma_f32 v[162:163], v[140:141], v[156:157], v[162:163]
	v_sub_f32_e32 v154, v76, v120
	v_sub_f32_e32 v156, v78, v120
	v_sub_f32_e32 v155, v70, v120
	v_sub_f32_e32 v157, v106, v120
	v_pk_mul_f32 v[154:155], v[120:121], v[154:155] op_sel:[1,0]
	v_pk_mul_f32 v[70:71], v[120:121], v[156:157] op_sel:[1,0]
	s_waitcnt vmcnt(0)
; DI unsigned pkh2(float lo, float hi) { return __builtin_bit_cast(unsigned, __builtin_amdgcn_cvt_pkrtz(lo, hi)); }
; DI void lnmod_phase(const Args& A, LAS unsigned char* lds, int tid, int bid, int G, bool init, int l_norm, int i_norm, int l_mod, int i_mod, bool want_dt, int nrows, bool ctx_partial, const float* gprev, const float* bprev) {
;     ...
;             const float* t0 = (const float*)(A.ws + WS_T) + (size_t)(row - M_LAT) * DM; const float* t1 = t0 + (size_t)M_CTX * DM; const float* t2 = t1 + (size_t)M_CTX * DM; const float* t3 = t2 + (size_t)M_CTX * DM;
; #pragma unroll
;             for (int j = 0; j < 4; ++j) { v[j] = v[j] * ALPHA + (*(const f32x4*)(t0 + 256 * j + 4 * lane) + *(const f32x4*)(t1 + 256 * j + 4 * lane)) + (*(const f32x4*)(t2 + 256 * j + 4 * lane) + *(const f32x4*)(t3 + 256 * j + 4 * lane)); u32x2 w_; w_.x = pkh2(v[j].x, v[j].y); w_.y = pkh2(v[j].z, v[j].w); *(u32x2*)(xout + 256 * j + 4 * lane) = w_; }
	v_pk_fma_f32 v[156:157], v[154:155], v[164:165], v[168:169]
	v_lshlrev_b64 v[64:65], 12, v[146:147]
	v_lshl_add_u64 v[64:65], s[36:37], 0, v[64:65]
	v_lshlrev_b32_e32 v146, 2, v84
	v_lshl_add_u64 v[110:111], v[64:65], 0, v[146:147]
	v_add_co_u32_e32 v130, vcc, s7, v110
	global_load_dwordx4 v[120:123], v[110:111], off
	s_nop 1
	v_addc_co_u32_e32 v131, vcc, 0, v111, vcc
	global_load_dwordx4 v[124:127], v[130:131], off
	s_mov_b64 s[36:37], 0x800000
	v_lshl_add_u64 v[132:133], v[110:111], 0, s[36:37]
	s_mov_b64 s[36:37], 0x1000000
	v_lshl_add_u64 v[76:77], v[110:111], 0, s[36:37]
	s_mov_b64 s[36:37], 0x1800000
	v_lshl_add_u64 v[134:135], v[110:111], 0, s[36:37]
	s_mov_b32 s7, 0x1000000
	v_add_co_u32_e32 v136, vcc, s7, v110
	s_mov_b32 s7, 0x1800000
	s_nop 1
	v_addc_co_u32_e32 v137, vcc, 0, v111, vcc
	global_load_dwordx4 v[172:175], v[136:137], off
	v_add_co_u32_e32 v142, vcc, s7, v110
	s_nop 1
	v_addc_co_u32_e32 v143, vcc, 0, v111, vcc
	global_load_dwordx4 v[176:179], v[142:143], off
	global_load_dwordx4 v[180:183], v[110:111], off offset:1024
	global_load_dwordx4 v[184:187], v[132:133], off offset:1024
	global_load_dwordx4 v[188:191], v[76:77], off offset:1024
	global_load_dwordx4 v[192:195], v[134:135], off offset:1024
	global_load_dwordx4 v[196:199], v[110:111], off offset:2048
	global_load_dwordx4 v[200:203], v[132:133], off offset:2048
	global_load_dwordx4 v[204:207], v[76:77], off offset:2048
	global_load_dwordx4 v[218:221], v[134:135], off offset:2048
	global_load_dwordx4 v[222:225], v[110:111], off offset:3072
	global_load_dwordx4 v[226:229], v[132:133], off offset:3072
	global_load_dwordx4 v[230:233], v[76:77], off offset:3072
	global_load_dwordx4 v[234:237], v[134:135], off offset:3072
	s_nop 0
	v_pk_fma_f32 v[70:71], v[70:71], v[166:167], v[170:171]
	s_mov_b32 s36, 0x3fd744fd
	s_waitcnt vmcnt(14)
	v_pk_add_f32 v[130:131], v[122:123], v[126:127]
	v_pk_add_f32 v[106:107], v[120:121], v[124:125]
	v_pk_fma_f32 v[130:131], v[114:115], s[36:37], v[130:131] op_sel_hi:[1,0,1]
	v_pk_fma_f32 v[114:115], v[128:129], s[36:37], v[106:107] op_sel_hi:[1,0,1]
	s_nop 0
	s_mov_b32 s7, 0x21200000
	s_nop 0
	s_waitcnt vmcnt(12)
	v_pk_add_f32 v[142:143], v[174:175], v[178:179]
	v_pk_add_f32 v[172:173], v[172:173], v[176:177]
	v_pk_add_f32 v[142:143], v[130:131], v[142:143]
	v_pk_add_f32 v[130:131], v[114:115], v[172:173]
	v_add_co_u32_e32 v114, vcc, s7, v104
	v_cvt_pkrtz_f16_f32 v172, v130, v131
	v_cvt_pkrtz_f16_f32 v173, v142, v143
	v_addc_co_u32_e32 v115, vcc, 0, v105, vcc
	global_store_dwordx2 v[114:115], v[172:173], off
	s_nop 0
	s_waitcnt vmcnt(11)
	v_pk_add_f32 v[182:183], v[182:183], v[186:187]
	v_pk_add_f32 v[180:181], v[180:181], v[184:185]
	v_pk_fma_f32 v[138:139], v[138:139], s[36:37], v[182:183] op_sel_hi:[1,0,1]
	v_pk_fma_f32 v[68:69], v[68:69], s[36:37], v[180:181] op_sel_hi:[1,0,1]
	s_waitcnt vmcnt(9)
	v_pk_add_f32 v[190:191], v[190:191], v[194:195]
	v_pk_add_f32 v[188:189], v[188:189], v[192:193]
	v_pk_add_f32 v[128:129], v[138:139], v[190:191]
	v_pk_add_f32 v[68:69], v[68:69], v[188:189]
	v_cvt_pkrtz_f16_f32 v139, v128, v129
	v_cvt_pkrtz_f16_f32 v138, v68, v69
	global_store_dwordx2 v[114:115], v[138:139], off offset:512
	s_waitcnt vmcnt(8)
	v_pk_add_f32 v[138:139], v[198:199], v[202:203]
	v_pk_add_f32 v[196:197], v[196:197], v[200:201]
	v_pk_fma_f32 v[138:139], v[162:163], s[36:37], v[138:139] op_sel_hi:[1,0,1]
	v_pk_fma_f32 v[200:201], v[160:161], s[36:37], v[196:197] op_sel_hi:[1,0,1]
	s_waitcnt vmcnt(6)
	v_pk_add_f32 v[206:207], v[206:207], v[220:221]
	v_pk_add_f32 v[204:205], v[204:205], v[218:219]
	v_pk_add_f32 v[206:207], v[138:139], v[206:207]
	v_pk_add_f32 v[204:205], v[200:201], v[204:205]
	v_cvt_pkrtz_f16_f32 v139, v206, v207
	v_cvt_pkrtz_f16_f32 v138, v204, v205
	global_store_dwordx2 v[114:115], v[138:139], off offset:1024
	s_nop 0
	s_waitcnt vmcnt(5)
	v_pk_add_f32 v[224:225], v[224:225], v[228:229]
	v_pk_add_f32 v[222:223], v[222:223], v[226:227]
	v_pk_fma_f32 v[70:71], v[70:71], s[36:37], v[224:225] op_sel_hi:[1,0,1]
	v_pk_fma_f32 v[156:157], v[156:157], s[36:37], v[222:223] op_sel_hi:[1,0,1]
	s_nop 0
	s_waitcnt vmcnt(3)
	v_pk_add_f32 v[236:237], v[232:233], v[236:237]
	v_pk_add_f32 v[234:235], v[230:231], v[234:235]
	v_pk_add_f32 v[236:237], v[70:71], v[236:237]
	v_pk_add_f32 v[234:235], v[156:157], v[234:235]
	v_cvt_pkrtz_f16_f32 v157, v236, v237
	v_cvt_pkrtz_f16_f32 v156, v234, v235
	global_store_dwordx2 v[114:115], v[156:157], off offset:1536
	v_mov_b32_e32 v230, v131
	v_mov_b32_e32 v231, v142
	v_mov_b32_e32 v131, v143
	v_mov_b32_e32 v156, v69
	v_mov_b32_e32 v157, v128
	v_mov_b32_e32 v69, v129
	v_mov_b32_e32 v70, v235
	v_mov_b32_e32 v142, v237
	v_mov_b32_e32 v64, v130
	v_mov_b32_e32 v65, v131
	v_mov_b32_e32 v66, v156
	v_mov_b32_e32 v67, v157
	v_mov_b32_e32 v72, v204
	v_mov_b32_e32 v73, v205
	v_mov_b32_e32 v74, v206
	v_mov_b32_e32 v75, v207
	v_mov_b32_e32 v76, v234
	v_mov_b32_e32 v78, v236
	v_mov_b32_e32 v106, v142
	v_mov_b32_e32 v108, v230
	v_mov_b32_e32 v109, v231

; DI void lnmod_phase(const Args& A, LAS unsigned char* lds, int tid, int bid, int G, bool init, int l_norm, int i_norm, int l_mod, int i_mod, bool want_dt, int nrows, bool ctx_partial, const float* gprev, const float* bprev) {
;     ...
;         if (l_mod >= 0) {
;             const int mi = row < M_LAT ? (row >> 12) : 8;
;             const float* mp = MOD + ((size_t)l_mod * 9 + mi) * 9216 + i_mod * 3072;
;             if (mi != mi_cur) { mi_cur = mi;
; #pragma unroll
;                 for (int j = 0; j < 4; ++j) { shv[j] = *(const f32x4*)(mp + 256 * j + 4 * lane); sclv[j] = *(const f32x4*)(mp + 1024 + 256 * j + 4 * lane) + 1.0f; } }
.LBB0_239:
	s_andn2_b64 vcc, exec, s[16:17]
	s_cbranch_vccnz .LBB0_228
	v_min_i32_e32 v106, 0x8000, v118
	v_ashrrev_i32_e32 v106, 12, v106
	s_mov_b64 vcc, s[76:77]
	s_and_saveexec_b64 s[0:1], vcc
	s_cbranch_execz .LBB0_227
	v_readlane_b32 s36, v253, 23
	v_readlane_b32 s38, v253, 25
	v_readlane_b32 s39, v253, 26
	v_readlane_b32 s37, v253, 24
	s_waitcnt vmcnt(7)
	v_pk_add_f32 v[50:51], v[50:51], 1.0 op_sel_hi:[1,0]
	v_pk_add_f32 v[48:49], v[48:49], 1.0 op_sel_hi:[1,0]
	s_waitcnt vmcnt(6)
	v_pk_add_f32 v[54:55], v[54:55], 1.0 op_sel_hi:[1,0]
	v_pk_add_f32 v[52:53], v[52:53], 1.0 op_sel_hi:[1,0]
	s_waitcnt vmcnt(5)
	v_pk_add_f32 v[58:59], v[58:59], 1.0 op_sel_hi:[1,0]
	v_pk_add_f32 v[56:57], v[56:57], 1.0 op_sel_hi:[1,0]
	s_waitcnt vmcnt(4)
	v_pk_add_f32 v[62:63], v[62:63], 1.0 op_sel_hi:[1,0]
	v_pk_add_f32 v[60:61], v[60:61], 1.0 op_sel_hi:[1,0]
	s_branch .LBB0_227

; DI void lnmod_phase(const Args& A, LAS unsigned char* lds, int tid, int bid, int G, bool init, int l_norm, int i_norm, int l_mod, int i_mod, bool want_dt, int nrows, bool ctx_partial, const float* gprev, const float* bprev) {
;     ...
;         if (l_mod >= 0) {
;             const int mi = row < M_LAT ? (row >> 12) : 8;
;             const float* mp = MOD + ((size_t)l_mod * 9 + mi) * 9216 + i_mod * 3072;
;             if (mi != mi_cur) { mi_cur = mi;
; #pragma unroll
;                 for (int j = 0; j < 4; ++j) { shv[j] = *(const f32x4*)(mp + 256 * j + 4 * lane); sclv[j] = *(const f32x4*)(mp + 1024 + 256 * j + 4 * lane) + 1.0f; } }
.LBB0_282:
	s_or_b64 exec, exec, s[4:5]
	s_mov_b64 s[76:77], 0
	s_andn2_b64 vcc, exec, s[2:3]
	s_cbranch_vccnz .Llnmi_skip2
	v_min_i32_e32 v248, 0x8000, v84
	v_ashrrev_i32_e32 v248, 12, v248
	v_cmp_ne_u32_e32 vcc, v248, v85
	s_mov_b64 s[76:77], vcc
	s_and_saveexec_b64 s[78:79], vcc
	s_cbranch_execz .Llnmi_done2
	v_readlane_b32 s80, v252, 7
	v_readlane_b32 s81, v252, 8
	v_ashrrev_i32_e32 v249, 31, v248
	v_lshl_add_u64 v[32:33], s[16:17], 0, v[248:249]
	v_lshlrev_b32_e32 v246, 2, v66
	v_mov_b32_e32 v247, v147
	v_mov_b64_e32 v[34:35], s[80:81]
	v_mad_u64_u32 v[34:35], s[82:83], v32, s94, v[34:35]
	v_mad_i32_i24 v35, v33, s94, v35
	v_lshl_add_u64 v[32:33], v[34:35], 0, v[246:247]
	s_mov_b64 s[82:83], 0x1000
	v_lshl_add_u64 v[34:35], v[32:33], 0, s[82:83]
	global_load_dwordx4 v[48:51], v[34:35], off offset:1024
	global_load_dwordx4 v[52:55], v[34:35], off offset:2048
	v_mov_b32_e32 v85, v248
	global_load_dwordx4 v[56:59], v[34:35], off
	global_load_dwordx4 v[60:63], v[34:35], off offset:3072
	global_load_dwordx4 v[44:47], v[32:33], off
	global_load_dwordx4 v[40:43], v[32:33], off offset:1024
	global_load_dwordx4 v[36:39], v[32:33], off offset:2048
	global_load_dwordx4 v[32:35], v[32:33], off offset:3072

; DI float hlo(unsigned u) { return (float)__builtin_bit_cast(f16x2_t, u).x; }
; DI float hhi(unsigned u) { return (float)__builtin_bit_cast(f16x2_t, u).y; }
; DI void lnmod_phase(const Args& A, LAS unsigned char* lds, int tid, int bid, int G, bool init, int l_norm, int i_norm, int l_mod, int i_mod, bool want_dt, int nrows, bool ctx_partial, const float* gprev, const float* bprev) {
;     ...
;         for (int j = 0; j < 4; ++j) v[j] = init ? fn[j] : (f32x4){hlo(un[j].x), hhi(un[j].x), hlo(un[j].y), hhi(un[j].y)};
;         { const int rown = row + G * 8;
;           if (rown < nrows) {
;               if (init) { const float* xin = rown < M_LAT ? A.in[I_X] + (size_t)rown * DM : A.in[I_CTX] + (size_t)(rown - M_LAT) * DM;
; #pragma unroll
;                   for (int j = 0; j < 4; ++j) fn[j] = *(const f32x4*)(xin + 256 * j + 4 * lane); }
;               else {
; #pragma unroll
;                   for (int j = 0; j < 4; ++j) un[j] = *(const u32x2*)(X16 + (size_t)rown * DM + 256 * j + 4 * lane); } } }
;         f32x2* STAT = (f32x2*)(A.ws + WS_STAT);
;         if (ctx_partial && row >= M_LAT) {
;             { const f32x2 st = STAT[row];
; #pragma unroll
;               for (int j = 0; j < 4; ++j) v[j] = (v[j] - st.x) * st.y * *(const f32x4*)(gprev + 256 * j + 4 * lane) + *(const f32x4*)(bprev + 256 * j + 4 * lane); }
.Llnmi_skip2:
	v_cvt_f32_f16_sdwa v104, v90 dst_sel:DWORD dst_unused:UNUSED_PAD src0_sel:WORD_1
	v_cvt_f32_f16_e32 v88, v90
	v_cvt_f32_f16_sdwa v89, v91 dst_sel:DWORD dst_unused:UNUSED_PAD src0_sel:WORD_1
	v_cvt_f32_f16_e32 v105, v91
	v_cvt_f32_f16_sdwa v100, v92 dst_sel:DWORD dst_unused:UNUSED_PAD src0_sel:WORD_1
	v_cvt_f32_f16_e32 v90, v92
	v_cvt_f32_f16_sdwa v91, v93 dst_sel:DWORD dst_unused:UNUSED_PAD src0_sel:WORD_1
	v_cvt_f32_f16_e32 v101, v93
	v_cvt_f32_f16_sdwa v95, v96 dst_sel:DWORD dst_unused:UNUSED_PAD src0_sel:WORD_1
	v_cvt_f32_f16_e32 v94, v96
	v_cvt_f32_f16_sdwa v93, v97 dst_sel:DWORD dst_unused:UNUSED_PAD src0_sel:WORD_1
	v_cvt_f32_f16_e32 v92, v97
	v_cvt_f32_f16_sdwa v102, v86 dst_sel:DWORD dst_unused:UNUSED_PAD src0_sel:WORD_1
	v_cvt_f32_f16_e32 v98, v86
	v_cvt_f32_f16_sdwa v106, v87 dst_sel:DWORD dst_unused:UNUSED_PAD src0_sel:WORD_1
	v_cvt_f32_f16_e32 v96, v87
	s_movk_i32 s4, 0x7fff
	v_cmp_lt_i32_e32 vcc, s4, v84
	v_readlane_b32 s4, v253, 37
	v_readlane_b32 s28, v253, 23
	v_readlane_b32 s5, v253, 38
	v_readlane_b32 s30, v253, 25
	v_readlane_b32 s31, v253, 26
	s_and_b64 s[24:25], s[4:5], vcc
	v_readlane_b32 s29, v253, 24
	v_lshl_add_u64 v[86:87], s[30:31], 0, v[64:65]
	s_and_saveexec_b64 s[4:5], s[24:25]
	s_cbranch_execz .LBB0_284
	v_readlane_b32 s26, v253, 25
	v_readlane_b32 s27, v253, 26
	v_add_u32_e32 v146, 0xffff8000, v84
	s_nop 1
	v_lshl_add_u64 v[108:109], s[26:27], 0, v[74:75]
	global_load_dwordx2 v[116:117], v[108:109], off
	v_readlane_b32 s24, v251, 61
	v_readlane_b32 s25, v251, 62
	s_mov_b32 s9, 0x800000
	global_load_dwordx4 v[124:127], v[68:69], off
	global_load_dwordx4 v[112:115], v[70:71], off
	global_load_dwordx4 v[128:131], v[68:69], off offset:1024
	global_load_dwordx4 v[132:135], v[70:71], off offset:1024
	global_load_dwordx4 v[136:139], v[68:69], off offset:2048
	global_load_dwordx4 v[140:143], v[70:71], off offset:2048
	global_load_dwordx4 v[154:157], v[68:69], off offset:3072
	global_load_dwordx4 v[160:163], v[70:71], off offset:3072
	s_waitcnt vmcnt(8)
	v_sub_f32_e32 v109, v104, v116
	v_sub_f32_e32 v108, v88, v116
	v_sub_f32_e32 v88, v105, v116
	v_pk_mul_f32 v[104:105], v[116:117], v[108:109] op_sel:[1,0]
	v_sub_f32_e32 v89, v89, v116
	v_pk_mul_f32 v[88:89], v[116:117], v[88:89] op_sel:[1,0]
	v_sub_f32_e32 v91, v91, v116
	v_sub_f32_e32 v95, v95, v116
	v_sub_f32_e32 v94, v94, v116
	v_sub_f32_e32 v93, v93, v116
	v_sub_f32_e32 v92, v92, v116
	v_sub_f32_e32 v99, v102, v116
	v_sub_f32_e32 v98, v98, v116
	v_sub_f32_e32 v97, v106, v116
	v_sub_f32_e32 v96, v96, v116
	v_pk_mul_f32 v[106:107], v[116:117], v[98:99] op_sel:[1,0]
	s_waitcnt vmcnt(6)
	v_pk_fma_f32 v[120:121], v[124:125], v[104:105], v[112:113]
	v_pk_fma_f32 v[88:89], v[126:127], v[88:89], v[114:115]
	v_sub_f32_e32 v105, v100, v116
	v_sub_f32_e32 v104, v90, v116
	v_sub_f32_e32 v90, v101, v116
	v_pk_mul_f32 v[100:101], v[116:117], v[90:91] op_sel:[1,0]
	v_pk_mul_f32 v[90:91], v[116:117], v[104:105] op_sel:[1,0]
	v_pk_mul_f32 v[104:105], v[116:117], v[94:95] op_sel:[1,0]
	s_waitcnt vmcnt(4)
	v_pk_fma_f32 v[90:91], v[90:91], v[128:129], v[132:133]
	v_pk_fma_f32 v[128:129], v[100:101], v[130:131], v[134:135]
	v_pk_mul_f32 v[100:101], v[116:117], v[92:93] op_sel:[1,0]
	s_waitcnt vmcnt(2)
	v_pk_fma_f32 v[136:137], v[104:105], v[136:137], v[140:141]
	v_pk_fma_f32 v[138:139], v[100:101], v[138:139], v[142:143]
	v_pk_mul_f32 v[104:105], v[116:117], v[96:97] op_sel:[1,0]
	s_waitcnt vmcnt(0)
; DI unsigned pkh2(float lo, float hi) { return __builtin_bit_cast(unsigned, __builtin_amdgcn_cvt_pkrtz(lo, hi)); }
; DI void lnmod_phase(const Args& A, LAS unsigned char* lds, int tid, int bid, int G, bool init, int l_norm, int i_norm, int l_mod, int i_mod, bool want_dt, int nrows, bool ctx_partial, const float* gprev, const float* bprev) {
;     ...
;             const float* t0 = (const float*)(A.ws + WS_T) + (size_t)(row - M_LAT) * DM; const float* t1 = t0 + (size_t)M_CTX * DM; const float* t2 = t1 + (size_t)M_CTX * DM; const float* t3 = t2 + (size_t)M_CTX * DM;
; #pragma unroll
;             for (int j = 0; j < 4; ++j) { v[j] = v[j] * ALPHA + (*(const f32x4*)(t0 + 256 * j + 4 * lane) + *(const f32x4*)(t1 + 256 * j + 4 * lane)) + (*(const f32x4*)(t2 + 256 * j + 4 * lane) + *(const f32x4*)(t3 + 256 * j + 4 * lane)); u32x2 w_; w_.x = pkh2(v[j].x, v[j].y); w_.y = pkh2(v[j].z, v[j].w); *(u32x2*)(xout + 256 * j + 4 * lane) = w_; }
	v_pk_fma_f32 v[154:155], v[106:107], v[154:155], v[160:161]
	v_lshlrev_b64 v[100:101], 12, v[146:147]
	v_lshl_add_u64 v[100:101], s[24:25], 0, v[100:101]
	v_lshlrev_b32_e32 v146, 2, v66
	v_lshl_add_u64 v[106:107], v[100:101], 0, v[146:147]
	v_add_co_u32_e32 v124, vcc, s9, v106
	global_load_dwordx4 v[112:115], v[106:107], off
	s_nop 1
	v_addc_co_u32_e32 v125, vcc, 0, v107, vcc
	global_load_dwordx4 v[116:119], v[124:125], off
	s_mov_b64 s[24:25], 0x800000
	v_lshl_add_u64 v[110:111], v[106:107], 0, s[24:25]
	s_mov_b64 s[24:25], 0x1000000
	v_lshl_add_u64 v[126:127], v[106:107], 0, s[24:25]
	s_mov_b64 s[24:25], 0x1800000
	v_lshl_add_u64 v[132:133], v[106:107], 0, s[24:25]
	s_mov_b32 s9, 0x1000000
	v_add_co_u32_e32 v134, vcc, s9, v106
	s_nop 1
	v_addc_co_u32_e32 v135, vcc, 0, v107, vcc
	s_mov_b32 s9, 0x1800000
	global_load_dwordx4 v[140:143], v[134:135], off
	v_add_co_u32_e32 v164, vcc, s9, v106
	s_nop 1
	v_addc_co_u32_e32 v165, vcc, 0, v107, vcc
	global_load_dwordx4 v[166:169], v[164:165], off
	global_load_dwordx4 v[170:173], v[106:107], off offset:1024
	global_load_dwordx4 v[174:177], v[110:111], off offset:1024
	global_load_dwordx4 v[178:181], v[126:127], off offset:1024
	global_load_dwordx4 v[182:185], v[132:133], off offset:1024
	global_load_dwordx4 v[186:189], v[106:107], off offset:2048
	global_load_dwordx4 v[190:193], v[110:111], off offset:2048
	global_load_dwordx4 v[194:197], v[126:127], off offset:2048
	global_load_dwordx4 v[198:201], v[132:133], off offset:2048
	global_load_dwordx4 v[202:205], v[106:107], off offset:3072
	global_load_dwordx4 v[218:221], v[110:111], off offset:3072
	global_load_dwordx4 v[222:225], v[126:127], off offset:3072
	global_load_dwordx4 v[226:229], v[132:133], off offset:3072
	s_nop 0
	v_pk_fma_f32 v[156:157], v[104:105], v[156:157], v[162:163]
	s_mov_b32 s24, 0x3fd744fd
	s_waitcnt vmcnt(14)
	v_pk_add_f32 v[124:125], v[114:115], v[118:119]
	s_nop 0
	v_pk_fma_f32 v[88:89], v[88:89], s[24:25], v[124:125] op_sel_hi:[1,0,1]
	v_pk_add_f32 v[112:113], v[112:113], v[116:117]
	s_nop 0
	v_pk_fma_f32 v[120:121], v[120:121], s[24:25], v[112:113] op_sel_hi:[1,0,1]
	s_mov_b32 s9, 0x21200000
	s_nop 0
	s_waitcnt vmcnt(12)
	v_pk_add_f32 v[164:165], v[142:143], v[168:169]
	v_pk_add_f32 v[140:141], v[140:141], v[166:167]
	v_pk_add_f32 v[164:165], v[88:89], v[164:165]
	v_pk_add_f32 v[88:89], v[120:121], v[140:141]
	v_add_co_u32_e32 v140, vcc, s9, v86
	v_cvt_pkrtz_f16_f32 v142, v88, v89
	v_cvt_pkrtz_f16_f32 v143, v164, v165
	v_addc_co_u32_e32 v141, vcc, 0, v87, vcc
	global_store_dwordx2 v[140:141], v[142:143], off
	s_nop 0
	s_waitcnt vmcnt(11)
	v_pk_add_f32 v[172:173], v[172:173], v[176:177]
	v_pk_add_f32 v[170:171], v[170:171], v[174:175]
	v_pk_fma_f32 v[128:129], v[128:129], s[24:25], v[172:173] op_sel_hi:[1,0,1]
	v_pk_fma_f32 v[90:91], v[90:91], s[24:25], v[170:171] op_sel_hi:[1,0,1]
	s_waitcnt vmcnt(9)
	v_pk_add_f32 v[180:181], v[180:181], v[184:185]
	v_pk_add_f32 v[178:179], v[178:179], v[182:183]
	v_pk_add_f32 v[122:123], v[128:129], v[180:181]
	v_pk_add_f32 v[90:91], v[90:91], v[178:179]
	v_cvt_pkrtz_f16_f32 v129, v122, v123
	v_cvt_pkrtz_f16_f32 v128, v90, v91
	global_store_dwordx2 v[140:141], v[128:129], off offset:512
	s_waitcnt vmcnt(8)
	v_pk_add_f32 v[128:129], v[188:189], v[192:193]
	v_pk_add_f32 v[186:187], v[186:187], v[190:191]
	v_pk_fma_f32 v[128:129], v[138:139], s[24:25], v[128:129] op_sel_hi:[1,0,1]
	v_pk_fma_f32 v[190:191], v[136:137], s[24:25], v[186:187] op_sel_hi:[1,0,1]
	s_waitcnt vmcnt(6)
	v_pk_add_f32 v[196:197], v[196:197], v[200:201]
	v_pk_add_f32 v[198:199], v[194:195], v[198:199]
	v_pk_add_f32 v[194:195], v[128:129], v[196:197]
	v_pk_add_f32 v[196:197], v[190:191], v[198:199]
	v_cvt_pkrtz_f16_f32 v129, v194, v195
	v_cvt_pkrtz_f16_f32 v128, v196, v197
	global_store_dwordx2 v[140:141], v[128:129], off offset:1024
	s_nop 0
	s_waitcnt vmcnt(5)
	v_pk_add_f32 v[204:205], v[204:205], v[220:221]
	v_pk_add_f32 v[202:203], v[202:203], v[218:219]
	v_pk_fma_f32 v[204:205], v[156:157], s[24:25], v[204:205] op_sel_hi:[1,0,1]
	v_pk_fma_f32 v[202:203], v[154:155], s[24:25], v[202:203] op_sel_hi:[1,0,1]
	s_nop 0
	s_waitcnt vmcnt(3)
	v_pk_add_f32 v[224:225], v[224:225], v[228:229]
	v_pk_add_f32 v[226:227], v[222:223], v[226:227]
	v_pk_add_f32 v[222:223], v[204:205], v[224:225]
	v_pk_add_f32 v[224:225], v[202:203], v[226:227]
	v_cvt_pkrtz_f16_f32 v227, v222, v223
	v_cvt_pkrtz_f16_f32 v226, v224, v225
	global_store_dwordx2 v[140:141], v[226:227], off offset:1536
	v_mov_b32_e32 v228, v89
	v_mov_b32_e32 v229, v164
	v_mov_b32_e32 v89, v165
	v_mov_b32_e32 v164, v91
	v_mov_b32_e32 v165, v122
	v_mov_b32_e32 v91, v123
	v_mov_b32_e32 v226, v225
	v_mov_b32_e32 v202, v223
	v_mov_b32_e32 v92, v194
	v_mov_b32_e32 v93, v195
	v_mov_b32_e32 v94, v196
	v_mov_b32_e32 v95, v197
	v_mov_b32_e32 v96, v222
	v_mov_b32_e32 v98, v224
	v_mov_b32_e32 v100, v164
	v_mov_b32_e32 v101, v165
	v_mov_b32_e32 v102, v226
	v_mov_b32_e32 v104, v228
	v_mov_b32_e32 v105, v229
	v_mov_b32_e32 v106, v202

; DI void lnmod_phase(const Args& A, LAS unsigned char* lds, int tid, int bid, int G, bool init, int l_norm, int i_norm, int l_mod, int i_mod, bool want_dt, int nrows, bool ctx_partial, const float* gprev, const float* bprev) {
;     ...
;         if (l_mod >= 0) {
;             const int mi = row < M_LAT ? (row >> 12) : 8;
;             const float* mp = MOD + ((size_t)l_mod * 9 + mi) * 9216 + i_mod * 3072;
;             if (mi != mi_cur) { mi_cur = mi;
; #pragma unroll
;                 for (int j = 0; j < 4; ++j) { shv[j] = *(const f32x4*)(mp + 256 * j + 4 * lane); sclv[j] = *(const f32x4*)(mp + 1024 + 256 * j + 4 * lane) + 1.0f; } }
.LBB0_287:
	s_or_b64 exec, exec, s[4:5]
	v_min_i32_e32 v84, 0x8000, v84
	v_ashrrev_i32_e32 v84, 12, v84
	s_mov_b64 vcc, s[76:77]
	s_and_saveexec_b64 s[4:5], vcc
	s_cbranch_execz .LBB0_278
	v_readlane_b32 s24, v252, 7
	v_readlane_b32 s25, v252, 8
	s_waitcnt vmcnt(7)
	v_pk_add_f32 v[50:51], v[50:51], 1.0 op_sel_hi:[1,0]
	v_pk_add_f32 v[48:49], v[48:49], 1.0 op_sel_hi:[1,0]
	s_waitcnt vmcnt(6)
	v_pk_add_f32 v[54:55], v[54:55], 1.0 op_sel_hi:[1,0]
	v_pk_add_f32 v[52:53], v[52:53], 1.0 op_sel_hi:[1,0]
	s_waitcnt vmcnt(5)
	v_pk_add_f32 v[58:59], v[58:59], 1.0 op_sel_hi:[1,0]
	v_pk_add_f32 v[56:57], v[56:57], 1.0 op_sel_hi:[1,0]
	s_waitcnt vmcnt(4)
	v_pk_add_f32 v[62:63], v[62:63], 1.0 op_sel_hi:[1,0]
	v_pk_add_f32 v[60:61], v[60:61], 1.0 op_sel_hi:[1,0]
	s_branch .LBB0_278
